# v45 + RWKV fused group-norm epilogue: gate sigmoid/silu chain computed in the shadow of the LDS read
# speedup vs baseline: 1.0024x; 1.0024x over previous
; #define LAS __attribute__((address_space(3)))
; __device__ __forceinline__ unsigned pk2(float lo, float hi) { const bf2_t r = __builtin_convertvector((f32x2){lo, hi}, bf2_t); unsigned u; __builtin_memcpy(&u, &r, 4); return u; }
; __device__ __forceinline__ float bflo(unsigned u) { return __uint_as_float(u << 16); }
; __device__ __forceinline__ float bfhi(unsigned u) { return __uint_as_float(u & 0xFFFF0000u); }
; __device__ __forceinline__ float siluf_(float x) { return x * frcp(1.0f + __expf(-x)); }
; __device__ __forceinline__ void rwkv_chunk_item(const P& p, const Ctx& c, int seg, int w, bool save) {
;     ...
;     auto eload = [&](int ch) { const size_t rr = (size_t)b * SEGT + ch * 16 + et;
;         e_g = *(const u32x2*)(SG + rr * DMIX + ech); e_v = *(const u32x2*)(SV + rr * DMIX + ech); e_z = *(const u32x2*)(P2 + rr * P2W + 512 + ech); e_rkr = BRKR[(rr * 24 + hh) * 4 + 2]; };
;     auto efinish = [&](int ch) { const f32x4 o4 = *(const LAS f32x4*)(YB + et * 68 + eg * 4);
;         float s1 = (o4[0] + o4[1]) + (o4[2] + o4[3]), s2 = (o4[0] * o4[0] + o4[1] * o4[1]) + (o4[2] * o4[2] + o4[3] * o4[3]);
;         s1 = dpp_add<0xB1>(s1); s2 = dpp_add<0xB1>(s2); s1 = dpp_add<0x4E>(s1); s2 = dpp_add<0x4E>(s2); s1 = dpp_add<0x141>(s1); s2 = dpp_add<0x141>(s2); s1 = dpp_add<0x140>(s1); s2 = dpp_add<0x140>(s2);
;         const float mean = s1 * (1.0f / 64.0f), var = fmaxf(s2 * (1.0f / 64.0f) - mean * mean, 0.f), rs = rsqrtf(var + 64e-5f);
;         const float gg[4] = {bflo(e_g.x), bfhi(e_g.x), bflo(e_g.y), bfhi(e_g.y)}, vv[4] = {bflo(e_v.x), bfhi(e_v.x), bflo(e_v.y), bfhi(e_v.y)}, zz[4] = {bflo(e_z.x), bfhi(e_z.x), bflo(e_z.y), bfhi(e_z.y)};
;         float y[4];
; #pragma unroll
;         for (int j = 0; j < 4; ++j) y[j] = ((o4[j] - mean) * rs * elg[j] + elb[j] + e_rkr * vv[j]) * gg[j] * siluf_(zz[j]);
;         *(u32x2*)(Y + ((size_t)b * SEGT + ch * 16 + et) * DIN + ech) = (u32x2){pk2(y[0], y[1]), pk2(y[2], y[3])}; };
.LBB0_886:
	v_mov_b32_e32 v44, v55
	v_mov_b32_e32 v83, v63
	v_mov_b32_e32 v82, v59
	s_cmp_eq_u32 s86, 0
	s_waitcnt lgkmcnt(0)
	s_barrier
	s_cselect_b64 s[2:3], -1, 0
	s_xor_b64 s[4:5], s[6:7], -1
	s_or_b64 s[2:3], s[4:5], s[2:3]
	s_and_b64 vcc, exec, s[2:3]
	s_cbranch_vccnz .LBB0_888
	v_add_u32_e32 v22, v77, v78
	ds_read_b128 v[22:25], v22 offset:60672
	s_mov_b32 s2, 0x3c800000
	v_lshlrev_b32_e32 v56, 16, v42
	v_and_b32_e32 v57, 0xffff0000, v42
	v_lshlrev_b32_e32 v130, 16, v43
	v_and_b32_e32 v131, 0xffff0000, v43
	v_mul_f32_e32 v132, 0xbfb8aa3b, v56
	v_mul_f32_e32 v133, 0xbfb8aa3b, v57
	v_mul_f32_e32 v134, 0xbfb8aa3b, v130
	v_mul_f32_e32 v135, 0xbfb8aa3b, v131
	v_exp_f32_e32 v132, v132
	v_exp_f32_e32 v133, v133
	v_exp_f32_e32 v134, v134
	v_exp_f32_e32 v135, v135
	v_add_f32_e32 v132, 1.0, v132
	v_add_f32_e32 v133, 1.0, v133
	v_add_f32_e32 v134, 1.0, v134
	v_add_f32_e32 v135, 1.0, v135
	v_rcp_f32_e32 v132, v132
	v_rcp_f32_e32 v133, v133
	v_rcp_f32_e32 v134, v134
	v_rcp_f32_e32 v135, v135
	v_pk_mul_f32 v[136:137], v[132:133], v[56:57]
	v_pk_mul_f32 v[138:139], v[134:135], v[130:131]
	s_waitcnt lgkmcnt(0)
	v_mul_f32_e32 v46, v22, v22
	v_mul_f32_e32 v48, v23, v23
	v_mul_f32_e32 v50, v24, v24
	v_mul_f32_e32 v52, v25, v25
	v_mov_b32_e32 v47, v22
	v_mov_b32_e32 v49, v23
	v_mov_b32_e32 v51, v24
	v_mov_b32_e32 v53, v25
	v_pk_add_f32 v[46:47], v[46:47], v[48:49]
	v_pk_add_f32 v[48:49], v[50:51], v[52:53]
	v_lshlrev_b32_e32 v52, 16, v40
	v_pk_add_f32 v[46:47], v[46:47], v[48:49]
	v_and_b32_e32 v53, 0xffff0000, v40
	v_lshlrev_b32_e32 v50, 16, v38
	v_mov_b32_dpp v49, v47 quad_perm:[1,0,3,2] row_mask:0xf bank_mask:0xf bound_ctrl:1
	v_mov_b32_dpp v48, v46 quad_perm:[1,0,3,2] row_mask:0xf bank_mask:0xf bound_ctrl:1
	v_pk_add_f32 v[46:47], v[46:47], v[48:49]
	v_and_b32_e32 v51, 0xffff0000, v38
	s_nop 0
	v_mov_b32_dpp v49, v47 quad_perm:[2,3,0,1] row_mask:0xf bank_mask:0xf bound_ctrl:1
	v_mov_b32_dpp v48, v46 quad_perm:[2,3,0,1] row_mask:0xf bank_mask:0xf bound_ctrl:1
	v_pk_add_f32 v[46:47], v[46:47], v[48:49]
	s_nop 1
	v_mov_b32_dpp v49, v47 row_half_mirror row_mask:0xf bank_mask:0xf bound_ctrl:1
	v_mov_b32_dpp v48, v46 row_half_mirror row_mask:0xf bank_mask:0xf bound_ctrl:1
	v_pk_add_f32 v[46:47], v[46:47], v[48:49]
	s_nop 1
	v_mov_b32_dpp v49, v47 row_mirror row_mask:0xf bank_mask:0xf bound_ctrl:1
	v_mov_b32_dpp v48, v46 row_mirror row_mask:0xf bank_mask:0xf bound_ctrl:1
	v_pk_add_f32 v[46:47], v[46:47], v[48:49]
	s_nop 0
	v_pk_mul_f32 v[46:47], v[46:47], s[2:3] op_sel_hi:[1,0]
	s_nop 0
	v_fma_f32 v45, -v47, v47, v46
	v_max_f32_e32 v45, 0, v45
	v_add_f32_e32 v45, 0x3a27c5ac, v45
	v_cmp_gt_f32_e32 vcc, s51, v45
	v_mul_f32_e32 v48, 0x4b800000, v45
	v_pk_add_f32 v[22:23], v[22:23], v[46:47] op_sel:[0,1] neg_lo:[0,1] neg_hi:[0,1]
	v_cndmask_b32_e32 v45, v45, v48, vcc
	v_rsq_f32_e32 v45, v45
	v_pk_add_f32 v[24:25], v[24:25], v[46:47] op_sel:[0,1] neg_lo:[0,1] neg_hi:[0,1]
	v_mul_f32_e32 v48, 0x45800000, v45
	v_cndmask_b32_e32 v48, v45, v48, vcc
	v_pk_mul_f32 v[22:23], v[22:23], v[48:49] op_sel_hi:[1,0]
	v_pk_mul_f32 v[24:25], v[24:25], v[48:49] op_sel_hi:[1,0]
	v_pk_fma_f32 v[22:23], v[14:15], v[22:23], v[18:19]
	v_pk_fma_f32 v[22:23], v[2:3], v[52:53], v[22:23] op_sel_hi:[0,1,1]
	v_pk_mul_f32 v[22:23], v[22:23], v[50:51]
	v_lshlrev_b32_e32 v52, 16, v41
	v_and_b32_e32 v53, 0xffff0000, v41
	v_pk_fma_f32 v[24:25], v[16:17], v[24:25], v[20:21]
	v_pk_mul_f32 v[22:23], v[136:137], v[22:23]
	v_lshlrev_b32_e32 v50, 16, v39
	v_and_b32_e32 v51, 0xffff0000, v39
	v_pk_fma_f32 v[24:25], v[2:3], v[52:53], v[24:25] op_sel_hi:[0,1,1]
	v_pk_mul_f32 v[24:25], v[24:25], v[50:51]
	v_cvt_pk_bf16_f32 v22, v22, v23
	s_nop 0
	v_pk_mul_f32 v[24:25], v[138:139], v[24:25]
	s_nop 0
	v_cvt_pk_bf16_f32 v23, v24, v25
	v_lshlrev_b64 v[24:25], 12, v[4:5]
	v_lshl_add_u64 v[24:25], v[30:31], 0, v[24:25]
	global_store_dwordx2 v[24:25], v[22:23], off
